# phase_filters t-loop: each lane loads 1/8 of the H2 row (prefetched), weights held in registers, 8 partial sums reduce-scattered with DPP; f32, only dot-product summation order changes
# speedup vs baseline: 1.0152x; 1.0047x over previous
.LBB0_129:
	v_mov_b32_e32 v0, 0x21c90
	s_barrier
	s_lshr_b32 s100, s26, 1
	s_and_b32 s100, s100, 0x80
	s_lshl_b32 s101, s26, 1
	s_and_b32 s101, s101, 0x100
	s_or_b32 s100, s100, s101
	s_andn2_b32 s101, s26, 0x180
	s_or_b32 s100, s100, s101
	s_lshl_b32 s36, s100, 3
	v_add_u32_e32 v0, 0, v0
	s_ashr_i32 s8, s100, 8
	s_and_b32 s27, s36, 0x3f8
	s_and_b32 s33, s100, 0x80
	ds_read_b64 v[0:1], v0
	s_cmp_eq_u32 s33, 0
	s_cselect_b64 s[10:11], -1, 0
	s_and_b64 s[12:13], s[10:11], exec
	s_cselect_b32 s35, s20, 0x1000
	s_ashr_i32 s9, s8, 31
	s_waitcnt lgkmcnt(0)
	v_readfirstlane_b32 s17, v0
	s_lshl_b64 s[12:13], s[8:9], 18
	v_readfirstlane_b32 s16, v1
	s_add_u32 s12, s17, s12
	s_addc_u32 s13, s16, s13
	v_lshl_add_u64 v[0:1], s[12:13], 0, v[72:73]
	s_lshl_b32 s48, s27, 2
	v_lshl_add_u64 v[0:1], v[0:1], 0, s[48:49]
	v_lshl_add_u64 v[0:1], v[0:1], 0, v[74:75]
	global_load_dword v0, v[0:1], off
	v_mov_b32_e32 v1, 0x21ca0
	v_cmp_gt_i32_e32 vcc, s35, v66
	v_mov_b32_e32 v70, v71
	s_waitcnt vmcnt(0)
	ds_write_b32 v69, v0
	s_waitcnt lgkmcnt(0)
	s_barrier
	s_nop 0
	v_add_u32_e32 v0, 0, v1
	ds_read_b64 v[0:1], v0
	s_waitcnt lgkmcnt(0)
	v_readfirstlane_b32 s17, v1
	v_readfirstlane_b32 s16, v0
	s_and_saveexec_b64 s[12:13], vcc
	s_cbranch_execz .LBB0_133
	s_and_b32 s9, s36, 0x200
	s_lshl_b32 s37, s8, 10
	s_and_b32 s36, s36, 0x1f8
	s_or_b32 s9, s9, s37
	v_or_b32_e32 v0, s36, v68
	v_or_b32_e32 v0, s9, v0
	v_ashrrev_i32_e32 v1, 31, v0
	v_lshl_add_u64 v[0:1], v[0:1], 2, s[16:17]
	global_load_dword v2, v[0:1], off
	s_lshl_b32 s9, s100, 1
	s_lshr_b32 s40, s35, 1
	s_and_b32 s41, s9, 0x100
	s_and_b64 s[36:37], s[10:11], exec
	s_mul_i32 s39, s8, 0x1100
	s_cselect_b32 s36, 8, 12
	s_sub_i32 s9, 0, s40
	s_mul_hi_i32 s38, s8, 0x1100
	v_lshlrev_b32_e32 v0, s36, v68
	s_add_u32 s36, s41, s39
	v_cvt_f32_u32_e32 v132, s35
	s_addc_u32 s37, 0, s38
	v_lshl_add_u32 v133, v0, 2, v128
	v_lshl_add_u64 v[0:1], s[36:37], 0, v[66:67]
	v_lshlrev_b64 v[0:1], 8, v[0:1]
	v_mov_b32_e32 v70, 0
	s_mov_b64 s[16:17], 0
	v_lshl_add_u64 v[76:77], s[4:5], 0, v[0:1]
	v_mov_b32_e32 v135, v66
	s_waitcnt vmcnt(0)
	v_and_b32_e32 v134, 0x7fffffff, v2
	v_lshlrev_b32_e32 v26, 7, v68
	v_xor_b32_e32 v27, 0, v68
	v_lshl_add_u32 v27, v27, 2, v26
	v_add_u32_e32 v28, 0x400, v27
	ds_read2_b32 v[78:79], v27 offset1:8
	ds_read2_b32 v[80:81], v27 offset0:16 offset1:24
	ds_read2_b32 v[82:83], v28 offset1:8
	ds_read2_b32 v[84:85], v28 offset0:16 offset1:24
	v_xor_b32_e32 v29, 1, v68
	v_lshl_add_u32 v29, v29, 2, v26
	v_add_u32_e32 v30, 0x400, v29
	ds_read2_b32 v[86:87], v29 offset1:8
	ds_read2_b32 v[88:89], v29 offset0:16 offset1:24
	ds_read2_b32 v[90:91], v30 offset1:8
	ds_read2_b32 v[92:93], v30 offset0:16 offset1:24
	v_xor_b32_e32 v27, 2, v68
	v_lshl_add_u32 v27, v27, 2, v26
	v_add_u32_e32 v28, 0x400, v27
	ds_read2_b32 v[94:95], v27 offset1:8
	ds_read2_b32 v[96:97], v27 offset0:16 offset1:24
	ds_read2_b32 v[98:99], v28 offset1:8
	ds_read2_b32 v[100:101], v28 offset0:16 offset1:24
	v_xor_b32_e32 v29, 3, v68
	v_lshl_add_u32 v29, v29, 2, v26
	v_add_u32_e32 v30, 0x400, v29
	ds_read2_b32 v[102:103], v29 offset1:8
	ds_read2_b32 v[104:105], v29 offset0:16 offset1:24
	ds_read2_b32 v[106:107], v30 offset1:8
	ds_read2_b32 v[108:109], v30 offset0:16 offset1:24
	v_xor_b32_e32 v27, 4, v68
	v_lshl_add_u32 v27, v27, 2, v26
	v_add_u32_e32 v28, 0x400, v27
	ds_read2_b32 v[110:111], v27 offset1:8
	ds_read2_b32 v[112:113], v27 offset0:16 offset1:24
	ds_read2_b32 v[114:115], v28 offset1:8
	ds_read2_b32 v[116:117], v28 offset0:16 offset1:24
	v_xor_b32_e32 v29, 5, v68
	v_lshl_add_u32 v29, v29, 2, v26
	v_add_u32_e32 v30, 0x400, v29
	ds_read2_b32 v[118:119], v29 offset1:8
	ds_read2_b32 v[120:121], v29 offset0:16 offset1:24
	ds_read2_b32 v[122:123], v30 offset1:8
	ds_read2_b32 v[124:125], v30 offset0:16 offset1:24
	v_xor_b32_e32 v27, 6, v68
	v_lshl_add_u32 v27, v27, 2, v26
	v_add_u32_e32 v28, 0x400, v27
	ds_read2_b32 v[136:137], v27 offset1:8
	ds_read2_b32 v[138:139], v27 offset0:16 offset1:24
	ds_read2_b32 v[140:141], v28 offset1:8
	ds_read2_b32 v[142:143], v28 offset0:16 offset1:24
	v_xor_b32_e32 v29, 7, v68
	v_lshl_add_u32 v29, v29, 2, v26
	v_add_u32_e32 v30, 0x400, v29
	ds_read2_b32 v[144:145], v29 offset1:8
	ds_read2_b32 v[146:147], v29 offset0:16 offset1:24
	ds_read2_b32 v[148:149], v30 offset1:8
	ds_read2_b32 v[150:151], v30 offset0:16 offset1:24
	v_lshl_add_u64 v[24:25], v[74:75], 2, v[76:77]
	global_load_dwordx4 v[0:3], v[24:25], off offset:-248
	global_load_dwordx4 v[4:7], v[24:25], off offset:-120
	s_lshr_b32 s101, s35, 7
	s_waitcnt lgkmcnt(0)
.Lfilt_t_loop:
	v_lshl_add_u64 v[24:25], v[24:25], 0, s[6:7]
	global_load_dwordx4 v[8:11], v[24:25], off offset:-248
	global_load_dwordx4 v[12:15], v[24:25], off offset:-120
	v_add_u32_e32 v152, s9, v135
	v_cvt_f32_i32_e32 v152, v152
	v_add_u32_e32 v135, 64, v135
	v_and_b32_e32 v153, 0x7fffffff, v152
	v_div_scale_f32 v154, s[36:37], v132, v132, v153
	v_rcp_f32_e32 v155, v154
	v_div_scale_f32 v153, vcc, v153, v132, v153
	v_fma_f32 v156, -v154, v155, 1.0
	v_fmac_f32_e32 v155, v156, v155
	v_mul_f32_e32 v156, v153, v155
	v_fma_f32 v157, -v154, v156, v153
	v_fmac_f32_e32 v156, v157, v155
	v_fma_f32 v153, -v154, v156, v153
	v_div_fmas_f32 v153, v153, v155, v156
	v_div_fixup_f32 v152, v153, v132, |v152|
	v_mul_f32_e64 v152, v152, -v134
	v_mul_f32_e32 v153, 0x3fb8aa3b, v152
	v_fma_f32 v154, v152, s21, -v153
	v_rndne_f32_e32 v155, v153
	v_fmac_f32_e32 v154, 0x32a5705f, v152
	v_sub_f32_e32 v153, v153, v155
	v_add_f32_e32 v153, v153, v154
	v_cvt_i32_f32_e32 v155, v155
	v_exp_f32_e32 v153, v153
	v_cmp_ngt_f32_e32 vcc, s22, v152
	s_nop 0
	v_ldexp_f32 v153, v153, v155
	s_nop 0
	v_cndmask_b32_e32 v153, 0, v153, vcc
	v_cmp_nlt_f32_e32 vcc, s23, v152
	s_nop 1
	v_cndmask_b32_e32 v152, v130, v153, vcc
	s_waitcnt vmcnt(2)
	v_mul_f32_e32 v16, v0, v78
	v_mul_f32_e32 v17, v0, v86
	v_mul_f32_e32 v18, v0, v94
	v_mul_f32_e32 v19, v0, v102
	v_mul_f32_e32 v20, v0, v110
	v_mul_f32_e32 v21, v0, v118
	v_mul_f32_e32 v22, v0, v136
	v_mul_f32_e32 v23, v0, v144
	v_fmac_f32_e32 v16, v1, v79
	v_fmac_f32_e32 v17, v1, v87
	v_fmac_f32_e32 v18, v1, v95
	v_fmac_f32_e32 v19, v1, v103
	v_fmac_f32_e32 v20, v1, v111
	v_fmac_f32_e32 v21, v1, v119
	v_fmac_f32_e32 v22, v1, v137
	v_fmac_f32_e32 v23, v1, v145
	v_fmac_f32_e32 v16, v2, v80
	v_fmac_f32_e32 v17, v2, v88
	v_fmac_f32_e32 v18, v2, v96
	v_fmac_f32_e32 v19, v2, v104
	v_fmac_f32_e32 v20, v2, v112
	v_fmac_f32_e32 v21, v2, v120
	v_fmac_f32_e32 v22, v2, v138
	v_fmac_f32_e32 v23, v2, v146
	v_fmac_f32_e32 v16, v3, v81
	v_fmac_f32_e32 v17, v3, v89
	v_fmac_f32_e32 v18, v3, v97
	v_fmac_f32_e32 v19, v3, v105
	v_fmac_f32_e32 v20, v3, v113
	v_fmac_f32_e32 v21, v3, v121
	v_fmac_f32_e32 v22, v3, v139
	v_fmac_f32_e32 v23, v3, v147
	v_fmac_f32_e32 v16, v4, v82
	v_fmac_f32_e32 v17, v4, v90
	v_fmac_f32_e32 v18, v4, v98
	v_fmac_f32_e32 v19, v4, v106
	v_fmac_f32_e32 v20, v4, v114
	v_fmac_f32_e32 v21, v4, v122
	v_fmac_f32_e32 v22, v4, v140
	v_fmac_f32_e32 v23, v4, v148
	v_fmac_f32_e32 v16, v5, v83
	v_fmac_f32_e32 v17, v5, v91
	v_fmac_f32_e32 v18, v5, v99
	v_fmac_f32_e32 v19, v5, v107
	v_fmac_f32_e32 v20, v5, v115
	v_fmac_f32_e32 v21, v5, v123
	v_fmac_f32_e32 v22, v5, v141
	v_fmac_f32_e32 v23, v5, v149
	v_fmac_f32_e32 v16, v6, v84
	v_fmac_f32_e32 v17, v6, v92
	v_fmac_f32_e32 v18, v6, v100
	v_fmac_f32_e32 v19, v6, v108
	v_fmac_f32_e32 v20, v6, v116
	v_fmac_f32_e32 v21, v6, v124
	v_fmac_f32_e32 v22, v6, v142
	v_fmac_f32_e32 v23, v6, v150
	v_fmac_f32_e32 v16, v7, v85
	v_fmac_f32_e32 v17, v7, v93
	v_fmac_f32_e32 v18, v7, v101
	v_fmac_f32_e32 v19, v7, v109
	v_fmac_f32_e32 v20, v7, v117
	v_fmac_f32_e32 v21, v7, v125
	v_fmac_f32_e32 v22, v7, v143
	v_fmac_f32_e32 v23, v7, v151
	s_nop 1
	v_add_f32_dpp v16, v23, v16 row_half_mirror row_mask:0xf bank_mask:0xf
	v_add_f32_dpp v17, v22, v17 row_half_mirror row_mask:0xf bank_mask:0xf
	v_add_f32_dpp v18, v21, v18 row_half_mirror row_mask:0xf bank_mask:0xf
	v_add_f32_dpp v19, v20, v19 row_half_mirror row_mask:0xf bank_mask:0xf
	s_nop 0
	v_add_f32_dpp v16, v18, v16 quad_perm:[2,3,0,1] row_mask:0xf bank_mask:0xf
	v_add_f32_dpp v17, v19, v17 quad_perm:[2,3,0,1] row_mask:0xf bank_mask:0xf
	s_nop 1
	v_add_f32_dpp v16, v17, v16 quad_perm:[1,0,3,2] row_mask:0xf bank_mask:0xf
	v_mul_f32_e32 v26, v152, v16
	ds_write_b32 v133, v26
	v_add_f32_e64 v70, v70, |v26|
	v_add_u32_e32 v133, 0x100, v133
	s_cmp_eq_u32 s101, 1
	s_cselect_b32 vcc_lo, 0, 0x4000
	s_mov_b32 vcc_hi, 0
	v_lshl_add_u64 v[24:25], v[24:25], 0, vcc
	global_load_dwordx4 v[0:3], v[24:25], off offset:-248
	global_load_dwordx4 v[4:7], v[24:25], off offset:-120
	v_add_u32_e32 v152, s9, v135
	v_cvt_f32_i32_e32 v152, v152
	v_add_u32_e32 v135, 64, v135
	v_and_b32_e32 v153, 0x7fffffff, v152
	v_div_scale_f32 v154, s[36:37], v132, v132, v153
	v_rcp_f32_e32 v155, v154
	v_div_scale_f32 v153, vcc, v153, v132, v153
	v_fma_f32 v156, -v154, v155, 1.0
	v_fmac_f32_e32 v155, v156, v155
	v_mul_f32_e32 v156, v153, v155
	v_fma_f32 v157, -v154, v156, v153
	v_fmac_f32_e32 v156, v157, v155
	v_fma_f32 v153, -v154, v156, v153
	v_div_fmas_f32 v153, v153, v155, v156
	v_div_fixup_f32 v152, v153, v132, |v152|
	v_mul_f32_e64 v152, v152, -v134
	v_mul_f32_e32 v153, 0x3fb8aa3b, v152
	v_fma_f32 v154, v152, s21, -v153
	v_rndne_f32_e32 v155, v153
	v_fmac_f32_e32 v154, 0x32a5705f, v152
	v_sub_f32_e32 v153, v153, v155
	v_add_f32_e32 v153, v153, v154
	v_cvt_i32_f32_e32 v155, v155
	v_exp_f32_e32 v153, v153
	v_cmp_ngt_f32_e32 vcc, s22, v152
	s_nop 0
	v_ldexp_f32 v153, v153, v155
	s_nop 0
	v_cndmask_b32_e32 v153, 0, v153, vcc
	v_cmp_nlt_f32_e32 vcc, s23, v152
	s_nop 1
	v_cndmask_b32_e32 v152, v130, v153, vcc
	s_waitcnt vmcnt(2)
	v_mul_f32_e32 v16, v8, v78
	v_mul_f32_e32 v17, v8, v86
	v_mul_f32_e32 v18, v8, v94
	v_mul_f32_e32 v19, v8, v102
	v_mul_f32_e32 v20, v8, v110
	v_mul_f32_e32 v21, v8, v118
	v_mul_f32_e32 v22, v8, v136
	v_mul_f32_e32 v23, v8, v144
	v_fmac_f32_e32 v16, v9, v79
	v_fmac_f32_e32 v17, v9, v87
	v_fmac_f32_e32 v18, v9, v95
	v_fmac_f32_e32 v19, v9, v103
	v_fmac_f32_e32 v20, v9, v111
	v_fmac_f32_e32 v21, v9, v119
	v_fmac_f32_e32 v22, v9, v137
	v_fmac_f32_e32 v23, v9, v145
	v_fmac_f32_e32 v16, v10, v80
	v_fmac_f32_e32 v17, v10, v88
	v_fmac_f32_e32 v18, v10, v96
	v_fmac_f32_e32 v19, v10, v104
	v_fmac_f32_e32 v20, v10, v112
	v_fmac_f32_e32 v21, v10, v120
	v_fmac_f32_e32 v22, v10, v138
	v_fmac_f32_e32 v23, v10, v146
	v_fmac_f32_e32 v16, v11, v81
	v_fmac_f32_e32 v17, v11, v89
	v_fmac_f32_e32 v18, v11, v97
	v_fmac_f32_e32 v19, v11, v105
	v_fmac_f32_e32 v20, v11, v113
	v_fmac_f32_e32 v21, v11, v121
	v_fmac_f32_e32 v22, v11, v139
	v_fmac_f32_e32 v23, v11, v147
	v_fmac_f32_e32 v16, v12, v82
	v_fmac_f32_e32 v17, v12, v90
	v_fmac_f32_e32 v18, v12, v98
	v_fmac_f32_e32 v19, v12, v106
	v_fmac_f32_e32 v20, v12, v114
	v_fmac_f32_e32 v21, v12, v122
	v_fmac_f32_e32 v22, v12, v140
	v_fmac_f32_e32 v23, v12, v148
	v_fmac_f32_e32 v16, v13, v83
	v_fmac_f32_e32 v17, v13, v91
	v_fmac_f32_e32 v18, v13, v99
	v_fmac_f32_e32 v19, v13, v107
	v_fmac_f32_e32 v20, v13, v115
	v_fmac_f32_e32 v21, v13, v123
	v_fmac_f32_e32 v22, v13, v141
	v_fmac_f32_e32 v23, v13, v149
	v_fmac_f32_e32 v16, v14, v84
	v_fmac_f32_e32 v17, v14, v92
	v_fmac_f32_e32 v18, v14, v100
	v_fmac_f32_e32 v19, v14, v108
	v_fmac_f32_e32 v20, v14, v116
	v_fmac_f32_e32 v21, v14, v124
	v_fmac_f32_e32 v22, v14, v142
	v_fmac_f32_e32 v23, v14, v150
	v_fmac_f32_e32 v16, v15, v85
	v_fmac_f32_e32 v17, v15, v93
	v_fmac_f32_e32 v18, v15, v101
	v_fmac_f32_e32 v19, v15, v109
	v_fmac_f32_e32 v20, v15, v117
	v_fmac_f32_e32 v21, v15, v125
	v_fmac_f32_e32 v22, v15, v143
	v_fmac_f32_e32 v23, v15, v151
	s_nop 1
	v_add_f32_dpp v16, v23, v16 row_half_mirror row_mask:0xf bank_mask:0xf
	v_add_f32_dpp v17, v22, v17 row_half_mirror row_mask:0xf bank_mask:0xf
	v_add_f32_dpp v18, v21, v18 row_half_mirror row_mask:0xf bank_mask:0xf
	v_add_f32_dpp v19, v20, v19 row_half_mirror row_mask:0xf bank_mask:0xf
	s_nop 0
	v_add_f32_dpp v16, v18, v16 quad_perm:[2,3,0,1] row_mask:0xf bank_mask:0xf
	v_add_f32_dpp v17, v19, v17 quad_perm:[2,3,0,1] row_mask:0xf bank_mask:0xf
	s_nop 1
	v_add_f32_dpp v16, v17, v16 quad_perm:[1,0,3,2] row_mask:0xf bank_mask:0xf
	v_mul_f32_e32 v26, v152, v16
	ds_write_b32 v133, v26
	v_add_f32_e64 v70, v70, |v26|
	v_add_u32_e32 v133, 0x100, v133
	s_sub_u32 s101, s101, 1
	s_cmp_lg_u32 s101, 0
	s_cbranch_scc1 .Lfilt_t_loop
	s_waitcnt vmcnt(0)
	s_or_b64 exec, exec, s[16:17]
